# attention: key-block-0 softmax hoisted to the end of QK (older half), priorities QK=1, softmax head=0, P.V part=2
# speedup vs baseline: 1.0075x; 1.0025x over previous
.LBB0_1010:
	s_lshl_b32 s90, s90, 14
	s_add_i32 s90, s90, 0x12000
	v_add_u32_e32 v2, s90, v163
	ds_read_b128 v[222:225], v2
	ds_read_b128 v[226:229], v2 offset:4096
	ds_read_b128 v[230:233], v2 offset:8192
	ds_read_b128 v[234:237], v2 offset:12288
	v_add_u32_e32 v2, s90, v171
	ds_read_b128 v[238:241], v2
	ds_read_b128 v[242:245], v2 offset:4096
	ds_read_b128 v[246:249], v2 offset:8192
	ds_read_b128 v[250:253], v2 offset:12288
	v_exp_f32_e32 v2, v98
	v_exp_f32_e32 v4, v99
	v_exp_f32_e32 v5, v100
	v_exp_f32_e32 v6, v101
	v_add_f32_e32 v7, 0, v2
	v_exp_f32_e32 v8, v102
	v_add_f32_e32 v7, v4, v7
	v_exp_f32_e32 v9, v103
	v_add_f32_e32 v7, v5, v7
	v_exp_f32_e32 v10, v104
	v_add_f32_e32 v7, v6, v7
	v_exp_f32_e32 v11, v105
	v_add_f32_e32 v7, v8, v7
	v_exp_f32_e32 v16, v106
	v_add_f32_e32 v7, v9, v7
	v_exp_f32_e32 v106, v107
	v_add_f32_e32 v7, v10, v7
	v_exp_f32_e32 v107, v108
	v_add_f32_e32 v7, v11, v7
	v_exp_f32_e32 v108, v109
	v_add_f32_e32 v7, v16, v7
	v_exp_f32_e32 v109, v110
	v_add_f32_e32 v7, v106, v7
	v_exp_f32_e32 v110, v111
	v_add_f32_e32 v7, v107, v7
	v_exp_f32_e32 v111, v112
	v_add_f32_e32 v7, v108, v7
	v_exp_f32_e32 v112, v113
	v_add_f32_e32 v7, v109, v7
	v_add_f32_e32 v7, v110, v7
	v_add_f32_e32 v7, v111, v7
	v_cvt_pk_bf16_f32 v4, v2, v4
	v_add_f32_e32 v17, v112, v7
	v_cvt_pk_bf16_f32 v5, v5, v6
	v_cvt_pk_bf16_f32 v6, v8, v9
	v_cvt_pk_bf16_f32 v7, v10, v11
	v_cvt_pk_bf16_f32 v106, v16, v106
	v_cvt_pk_bf16_f32 v107, v107, v108
	v_cvt_pk_bf16_f32 v108, v109, v110
	v_cvt_pk_bf16_f32 v109, v111, v112
	s_setprio 2
	s_waitcnt lgkmcnt(7)
	v_mfma_f32_32x32x16_bf16 v[66:81], v[222:225], v[4:7], v[66:81]
	v_exp_f32_e32 v2, v82
	v_exp_f32_e32 v185, v83
	s_nop 0
	v_add_f32_e32 v199, v2, v185
	s_waitcnt lgkmcnt(6)
	v_mfma_f32_32x32x16_bf16 v[50:65], v[226:229], v[4:7], v[50:65]
	v_exp_f32_e32 v198, v84
	v_exp_f32_e32 v16, v85
	s_nop 0
	v_add_f32_e32 v8, v198, v16
	v_add_f32_e32 v9, v199, v17
	v_add_f32_e32 v201, v8, v9
	s_waitcnt lgkmcnt(5)
	v_mfma_f32_32x32x16_bf16 v[34:49], v[230:233], v[4:7], v[34:49]
	v_exp_f32_e32 v17, v86
	v_exp_f32_e32 v199, v87
	s_nop 0
	v_add_f32_e32 v203, v17, v199
	s_waitcnt lgkmcnt(4)
	v_mfma_f32_32x32x16_bf16 v[18:33], v[234:237], v[4:7], v[18:33]
	v_exp_f32_e32 v202, v88
	v_exp_f32_e32 v200, v89
	s_nop 0
	v_add_f32_e32 v8, v202, v200
	v_add_f32_e32 v9, v203, v201
	v_add_f32_e32 v205, v8, v9
	v_add_u32_e32 v82, s90, v172
	ds_read_b128 v[4:7], v82
	ds_read_b128 v[8:11], v82 offset:4096
	ds_read_b128 v[12:15], v82 offset:8192
	ds_read_b128 v[82:85], v82 offset:12288
	s_waitcnt lgkmcnt(7)
	v_mfma_f32_32x32x16_bf16 v[66:81], v[238:241], v[106:109], v[66:81]
	v_exp_f32_e32 v201, v90
	v_exp_f32_e32 v203, v91
	s_nop 0
	v_add_f32_e32 v207, v201, v203
	s_waitcnt lgkmcnt(6)
	v_mfma_f32_32x32x16_bf16 v[50:65], v[242:245], v[106:109], v[50:65]
	v_exp_f32_e32 v206, v92
	v_exp_f32_e32 v204, v93
	s_nop 0
	v_add_f32_e32 v86, v206, v204
	v_add_f32_e32 v87, v207, v205
	v_add_f32_e32 v111, v86, v87
	s_waitcnt lgkmcnt(5)
	v_mfma_f32_32x32x16_bf16 v[34:49], v[246:249], v[106:109], v[34:49]
	v_exp_f32_e32 v186, v94
	v_exp_f32_e32 v187, v95
	s_nop 0
	v_add_f32_e32 v113, v186, v187
	s_waitcnt lgkmcnt(4)
	v_mfma_f32_32x32x16_bf16 v[18:33], v[250:253], v[106:109], v[18:33]
	v_exp_f32_e32 v112, v96
	v_exp_f32_e32 v110, v97
	s_nop 0
	v_add_f32_e32 v86, v112, v110
	v_add_f32_e32 v87, v113, v111
	v_add_f32_e32 v102, v86, v87
	v_add_u32_e32 v98, s90, v173
	ds_read_b128 v[86:89], v98
	ds_read_b128 v[90:93], v98 offset:4096
	ds_read_b128 v[94:97], v98 offset:8192
	ds_read_b128 v[98:101], v98 offset:12288
	v_add_f32_e32 v178, v178, v102
	v_cvt_pk_bf16_f32 v102, v2, v185
	v_cvt_pk_bf16_f32 v103, v198, v16
	v_cvt_pk_bf16_f32 v104, v17, v199
	v_cvt_pk_bf16_f32 v105, v202, v200
	v_cvt_pk_bf16_f32 v106, v201, v203
	v_cvt_pk_bf16_f32 v107, v206, v204
	v_cvt_pk_bf16_f32 v108, v186, v187
	v_cvt_pk_bf16_f32 v109, v112, v110
	s_waitcnt lgkmcnt(7)
	v_mfma_f32_32x32x16_bf16 v[66:81], v[4:7], v[102:105], v[66:81]
	s_waitcnt lgkmcnt(6)
	v_mfma_f32_32x32x16_bf16 v[50:65], v[8:11], v[102:105], v[50:65]
	s_waitcnt lgkmcnt(5)
	v_mfma_f32_32x32x16_bf16 v[34:49], v[12:15], v[102:105], v[34:49]
	s_waitcnt lgkmcnt(4)
	v_mfma_f32_32x32x16_bf16 v[18:33], v[82:85], v[102:105], v[18:33]
	s_waitcnt lgkmcnt(0)
	v_mfma_f32_32x32x16_bf16 v[66:81], v[86:89], v[106:109], v[66:81]
	v_mfma_f32_32x32x16_bf16 v[50:65], v[90:93], v[106:109], v[50:65]
	v_mfma_f32_32x32x16_bf16 v[34:49], v[94:97], v[106:109], v[34:49]
	v_mfma_f32_32x32x16_bf16 v[18:33], v[98:101], v[106:109], v[18:33]

.LBB0_1025:
	s_lshl_b32 s0, s73, 14
	s_add_i32 s0, s0, 0x12000
	v_add_u32_e32 v2, s0, v163
	ds_read_b128 v[222:225], v2
	ds_read_b128 v[226:229], v2 offset:4096
	ds_read_b128 v[230:233], v2 offset:8192
	ds_read_b128 v[234:237], v2 offset:12288
	v_add_u32_e32 v2, s0, v171
	ds_read_b128 v[238:241], v2
	ds_read_b128 v[242:245], v2 offset:4096
	ds_read_b128 v[246:249], v2 offset:8192
	ds_read_b128 v[250:253], v2 offset:12288
	s_waitcnt lgkmcnt(7)
	v_mfma_f32_32x32x16_bf16 v[66:81], v[222:225], v[4:7], v[66:81]
	v_exp_f32_e32 v2, v82
	v_exp_f32_e32 v179, v83
	s_nop 0
	v_add_f32_e32 v193, v2, v179
	s_waitcnt lgkmcnt(6)
	v_mfma_f32_32x32x16_bf16 v[50:65], v[226:229], v[4:7], v[50:65]
	v_exp_f32_e32 v192, v84
	v_exp_f32_e32 v16, v85
	s_nop 0
	v_add_f32_e32 v8, v192, v16
	v_add_f32_e32 v9, v193, v17
	v_add_f32_e32 v195, v8, v9
	s_waitcnt lgkmcnt(5)
	v_mfma_f32_32x32x16_bf16 v[34:49], v[230:233], v[4:7], v[34:49]
	v_exp_f32_e32 v17, v86
	v_exp_f32_e32 v193, v87
	s_nop 0
	v_add_f32_e32 v197, v17, v193
	s_waitcnt lgkmcnt(4)
	v_mfma_f32_32x32x16_bf16 v[18:33], v[234:237], v[4:7], v[18:33]
	v_exp_f32_e32 v196, v88
	v_exp_f32_e32 v194, v89
	s_nop 0
	v_add_f32_e32 v8, v196, v194
	v_add_f32_e32 v9, v197, v195
	v_add_f32_e32 v199, v8, v9
	v_add_u32_e32 v82, s0, v172
	ds_read_b128 v[4:7], v82
	ds_read_b128 v[8:11], v82 offset:4096
	ds_read_b128 v[12:15], v82 offset:8192
	ds_read_b128 v[82:85], v82 offset:12288
	s_waitcnt lgkmcnt(7)
	v_mfma_f32_32x32x16_bf16 v[66:81], v[238:241], v[106:109], v[66:81]
	v_exp_f32_e32 v195, v90
	v_exp_f32_e32 v197, v91
	s_nop 0
	v_add_f32_e32 v201, v195, v197
	s_waitcnt lgkmcnt(6)
	v_mfma_f32_32x32x16_bf16 v[50:65], v[242:245], v[106:109], v[50:65]
	v_exp_f32_e32 v200, v92
	v_exp_f32_e32 v198, v93
	s_nop 0
	v_add_f32_e32 v86, v200, v198
	v_add_f32_e32 v87, v201, v199
	v_add_f32_e32 v111, v86, v87
	s_waitcnt lgkmcnt(5)
	v_mfma_f32_32x32x16_bf16 v[34:49], v[246:249], v[106:109], v[34:49]
	v_exp_f32_e32 v180, v94
	v_exp_f32_e32 v181, v95
	s_nop 0
	v_add_f32_e32 v113, v180, v181
	s_waitcnt lgkmcnt(4)
	v_mfma_f32_32x32x16_bf16 v[18:33], v[250:253], v[106:109], v[18:33]
	v_exp_f32_e32 v112, v96
	v_exp_f32_e32 v110, v97
	s_nop 0
	v_add_f32_e32 v86, v112, v110
	v_add_f32_e32 v87, v113, v111
	v_add_f32_e32 v102, v86, v87
	v_add_u32_e32 v98, s0, v173
	ds_read_b128 v[86:89], v98
	ds_read_b128 v[90:93], v98 offset:4096
	ds_read_b128 v[94:97], v98 offset:8192
	ds_read_b128 v[98:101], v98 offset:12288
	v_add_f32_e32 v178, v178, v102
	v_cvt_pk_bf16_f32 v102, v2, v179
	v_cvt_pk_bf16_f32 v103, v192, v16
	v_cvt_pk_bf16_f32 v104, v17, v193
	v_cvt_pk_bf16_f32 v105, v196, v194
	v_cvt_pk_bf16_f32 v106, v195, v197
	v_cvt_pk_bf16_f32 v107, v200, v198
	v_cvt_pk_bf16_f32 v108, v180, v181
	v_cvt_pk_bf16_f32 v109, v112, v110
	s_waitcnt lgkmcnt(7)
	v_mfma_f32_32x32x16_bf16 v[66:81], v[4:7], v[102:105], v[66:81]
	s_waitcnt lgkmcnt(6)
	v_mfma_f32_32x32x16_bf16 v[50:65], v[8:11], v[102:105], v[50:65]
	s_waitcnt lgkmcnt(5)
	v_mfma_f32_32x32x16_bf16 v[34:49], v[12:15], v[102:105], v[34:49]
	s_waitcnt lgkmcnt(4)
	v_mfma_f32_32x32x16_bf16 v[18:33], v[82:85], v[102:105], v[18:33]
	s_waitcnt lgkmcnt(0)
	v_mfma_f32_32x32x16_bf16 v[66:81], v[86:89], v[106:109], v[66:81]
	v_mfma_f32_32x32x16_bf16 v[50:65], v[90:93], v[106:109], v[50:65]
	v_mfma_f32_32x32x16_bf16 v[34:49], v[94:97], v[106:109], v[34:49]
	v_mfma_f32_32x32x16_bf16 v[18:33], v[98:101], v[106:109], v[18:33]

; #define LAS __attribute__((address_space(3)))
; __device__ __forceinline__ void attn_issue_k(const Frame& F, const unsigned char* ktile, LAS unsigned char* buf) {
;     unsigned lo = F.lane * 16; asm volatile("" : "+v"(lo));
; #pragma unroll
;     for (int j = 0; j < 3; ++j) __builtin_amdgcn_global_load_lds((const unsigned*)(ktile + (size_t)(F.wave * 3 + j) * 1024 + lo), (LAS unsigned*)(buf + (F.wave * 3 + j) * 1024), 16, 0, 0);
; }
.LBB0_1027:
	s_setprio 1
	s_min_u32 s75, s33, s45
	s_mul_i32 s0, s75, 0x6000
	s_add_u32 s0, s40, s0
	s_addc_u32 s1, s41, 0
	s_mul_i32 s88, s74, 0x6000
	v_mov_b32_e32 v2, v164
	s_add_i32 s88, s88, 0
	s_add_i32 m0, s88, s56
	s_add_u32 s98, s0, s8
	s_addc_u32 s99, s1, s9
	global_load_lds_dwordx4 v164, s[98:99]
	s_add_u32 s100, s0, s10
	s_addc_u32 s101, s1, s11
	s_add_i32 m0, s88, s57
	s_add_u32 s98, s0, s12
	s_addc_u32 s99, s1, s13
	global_load_lds_dwordx4 v164, s[100:101]
	s_add_i32 m0, s88, s58
	s_cmp_le_u32 s72, s70
	global_load_lds_dwordx4 v164, s[98:99]
	s_cselect_b64 s[0:1], -1, 0
	s_cmp_gt_u32 s72, s70
	s_cbranch_scc1 .LBB0_1029
	s_mul_i32 s88, s73, 0x6000
	v_add_u32_e32 v2, s88, v174
	v_add_u32_e32 v16, s88, v175
	ds_read_b128 v[4:7], v2
	ds_read_b128 v[8:11], v2 offset:12288
	ds_read_b128 v[12:15], v16
	ds_read_b128 v[180:183], v16 offset:12288
	v_add_u32_e32 v17, s88, v176
	v_add_u32_e32 v179, s88, v177
	ds_read_b128 v[184:187], v17
	ds_read_b128 v[188:191], v17 offset:12288
	ds_read_b128 v[192:195], v179
	ds_read_b128 v[196:199], v179 offset:12288
	ds_read_b128 v[200:203], v2 offset:128
	ds_read_b128 v[204:207], v2 offset:12416
	ds_read_b128 v[208:211], v16 offset:128
	ds_read_b128 v[212:215], v16 offset:12416
	s_waitcnt lgkmcnt(8)
	v_mfma_f32_32x32x16_bf16 v[98:113], v[4:7], v[114:117], 0
	v_mfma_f32_32x32x16_bf16 v[98:113], v[12:15], v[118:121], v[98:113]
	v_mfma_f32_32x32x16_bf16 v[82:97], v[8:11], v[114:117], 0
	v_mfma_f32_32x32x16_bf16 v[82:97], v[180:183], v[118:121], v[82:97]
	ds_read_b128 v[4:7], v17 offset:128
	ds_read_b128 v[8:11], v17 offset:12416
	ds_read_b128 v[12:15], v179 offset:128
	ds_read_b128 v[180:183], v179 offset:12416
	s_waitcnt lgkmcnt(8)
	v_mfma_f32_32x32x16_bf16 v[98:113], v[184:187], v[122:125], v[98:113]
	v_mfma_f32_32x32x16_bf16 v[98:113], v[192:195], v[126:129], v[98:113]
	v_mfma_f32_32x32x16_bf16 v[82:97], v[188:191], v[122:125], v[82:97]
	v_mfma_f32_32x32x16_bf16 v[82:97], v[196:199], v[126:129], v[82:97]
	ds_read_b128 v[184:187], v2 offset:256
	ds_read_b128 v[188:191], v2 offset:12544
	ds_read_b128 v[192:195], v16 offset:256
	ds_read_b128 v[196:199], v16 offset:12544
	s_waitcnt lgkmcnt(8)
	v_mfma_f32_32x32x16_bf16 v[98:113], v[200:203], v[130:133], v[98:113]
	v_mfma_f32_32x32x16_bf16 v[98:113], v[208:211], v[134:137], v[98:113]
	v_mfma_f32_32x32x16_bf16 v[82:97], v[204:207], v[130:133], v[82:97]
	v_mfma_f32_32x32x16_bf16 v[82:97], v[212:215], v[134:137], v[82:97]
	ds_read_b128 v[200:203], v17 offset:256
	ds_read_b128 v[204:207], v17 offset:12544
	ds_read_b128 v[208:211], v179 offset:256
	ds_read_b128 v[212:215], v179 offset:12544
	s_waitcnt lgkmcnt(8)
	v_mfma_f32_32x32x16_bf16 v[98:113], v[4:7], v[138:141], v[98:113]
	v_mfma_f32_32x32x16_bf16 v[98:113], v[12:15], v[142:145], v[98:113]
	v_mfma_f32_32x32x16_bf16 v[82:97], v[8:11], v[138:141], v[82:97]
	v_mfma_f32_32x32x16_bf16 v[82:97], v[180:183], v[142:145], v[82:97]
	s_waitcnt lgkmcnt(4)
	v_mfma_f32_32x32x16_bf16 v[98:113], v[184:187], v[146:149], v[98:113]
	v_mfma_f32_32x32x16_bf16 v[98:113], v[192:195], v[154:157], v[98:113]
	v_mfma_f32_32x32x16_bf16 v[82:97], v[188:191], v[146:149], v[82:97]
	v_mfma_f32_32x32x16_bf16 v[82:97], v[196:199], v[154:157], v[82:97]
	s_waitcnt lgkmcnt(0)
	v_mfma_f32_32x32x16_bf16 v[98:113], v[200:203], v[150:153], v[98:113]
	v_mfma_f32_32x32x16_bf16 v[98:113], v[208:211], v[158:161], v[98:113]
	v_mfma_f32_32x32x16_bf16 v[82:97], v[204:207], v[150:153], v[82:97]
	v_mfma_f32_32x32x16_bf16 v[82:97], v[212:215], v[158:161], v[82:97]
	s_setprio 0
	s_nop 11
	s_add_i32 s88, s72, 47
	s_cmp_le_u32 s88, s6
	s_cbranch_scc1 .Lmy_a_softmax0
	v_cmp_lt_i32_e32 vcc, -1, v170
	s_nop 1
	v_cndmask_b32_e32 v98, v167, v98, vcc
	v_cmp_lt_i32_e32 vcc, 31, v170
	s_nop 1
	v_cndmask_b32_e32 v82, v167, v82, vcc
	v_cmp_lt_i32_e32 vcc, 0, v170
	s_nop 1
	v_cndmask_b32_e32 v99, v167, v99, vcc
	v_cmp_lt_i32_e32 vcc, 32, v170
	s_nop 1
	v_cndmask_b32_e32 v83, v167, v83, vcc
	v_cmp_lt_i32_e32 vcc, 1, v170
	s_nop 1
	v_cndmask_b32_e32 v100, v167, v100, vcc
	v_cmp_lt_i32_e32 vcc, 33, v170
	s_nop 1
	v_cndmask_b32_e32 v84, v167, v84, vcc
	v_cmp_lt_i32_e32 vcc, 2, v170
	s_nop 1
	v_cndmask_b32_e32 v101, v167, v101, vcc
	v_cmp_lt_i32_e32 vcc, 34, v170
	s_nop 1
	v_cndmask_b32_e32 v85, v167, v85, vcc
	v_cmp_lt_i32_e32 vcc, 7, v170
	s_nop 1
	v_cndmask_b32_e32 v102, v167, v102, vcc
	v_cmp_lt_i32_e32 vcc, 39, v170
	s_nop 1
	v_cndmask_b32_e32 v86, v167, v86, vcc
	v_cmp_lt_i32_e32 vcc, 8, v170
	s_nop 1
	v_cndmask_b32_e32 v103, v167, v103, vcc
	v_cmp_lt_i32_e32 vcc, 40, v170
	s_nop 1
	v_cndmask_b32_e32 v87, v167, v87, vcc
	v_cmp_lt_i32_e32 vcc, 9, v170
	s_nop 1
	v_cndmask_b32_e32 v104, v167, v104, vcc
	v_cmp_lt_i32_e32 vcc, 41, v170
	s_nop 1
	v_cndmask_b32_e32 v88, v167, v88, vcc
	v_cmp_lt_i32_e32 vcc, 10, v170
	s_nop 1
	v_cndmask_b32_e32 v105, v167, v105, vcc
	v_cmp_lt_i32_e32 vcc, 42, v170
	s_nop 1
	v_cndmask_b32_e32 v89, v167, v89, vcc
	v_cmp_lt_i32_e32 vcc, 15, v170
	s_nop 1
	v_cndmask_b32_e32 v106, v167, v106, vcc
	v_cmp_lt_i32_e32 vcc, 47, v170
	s_nop 1
	v_cndmask_b32_e32 v90, v167, v90, vcc
	v_cmp_lt_i32_e32 vcc, 16, v170
	s_nop 1
	v_cndmask_b32_e32 v107, v167, v107, vcc
	v_cmp_lt_i32_e32 vcc, 48, v170
	s_nop 1
	v_cndmask_b32_e32 v91, v167, v91, vcc
	v_cmp_lt_i32_e32 vcc, 17, v170
	s_nop 1
	v_cndmask_b32_e32 v108, v167, v108, vcc
	v_cmp_lt_i32_e32 vcc, 49, v170
	s_nop 1
	v_cndmask_b32_e32 v92, v167, v92, vcc
	v_cmp_lt_i32_e32 vcc, 18, v170
	s_nop 1
	v_cndmask_b32_e32 v109, v167, v109, vcc
	v_cmp_lt_i32_e32 vcc, 50, v170
	s_nop 1
	v_cndmask_b32_e32 v93, v167, v93, vcc
	v_cmp_lt_i32_e32 vcc, 23, v170
	s_nop 1
	v_cndmask_b32_e32 v110, v167, v110, vcc
	v_cmp_lt_i32_e32 vcc, 55, v170
	s_nop 1
	v_cndmask_b32_e32 v94, v167, v94, vcc
	v_cmp_lt_i32_e32 vcc, 24, v170
	s_nop 1
	v_cndmask_b32_e32 v111, v167, v111, vcc
	v_cmp_lt_i32_e32 vcc, 56, v170
	s_nop 1
	v_cndmask_b32_e32 v95, v167, v95, vcc
	v_cmp_lt_i32_e32 vcc, 25, v170
	s_nop 1
	v_cndmask_b32_e32 v112, v167, v112, vcc
	v_cmp_lt_i32_e32 vcc, 57, v170
	s_nop 1
	v_cndmask_b32_e32 v96, v167, v96, vcc
	v_cmp_lt_i32_e32 vcc, 26, v170
	s_nop 1
	v_cndmask_b32_e32 v113, v167, v113, vcc
	v_cmp_lt_i32_e32 vcc, 58, v170
	s_nop 1
	v_cndmask_b32_e32 v97, v167, v97, vcc
.Lmy_a_softmax0:
	v_exp_f32_e32 v2, v98
	v_exp_f32_e32 v4, v99
	v_exp_f32_e32 v5, v100
	v_exp_f32_e32 v6, v101
	v_add_f32_e32 v7, 0, v2
	v_exp_f32_e32 v8, v102
	v_add_f32_e32 v7, v4, v7
	v_exp_f32_e32 v9, v103
	v_add_f32_e32 v7, v5, v7
	v_exp_f32_e32 v10, v104
	v_add_f32_e32 v7, v6, v7
	v_exp_f32_e32 v11, v105
	v_add_f32_e32 v7, v8, v7
	v_exp_f32_e32 v16, v106
	v_add_f32_e32 v7, v9, v7
	v_exp_f32_e32 v106, v107
	v_add_f32_e32 v7, v10, v7
	v_exp_f32_e32 v107, v108
	v_add_f32_e32 v7, v11, v7
	v_exp_f32_e32 v108, v109
	v_add_f32_e32 v7, v16, v7
	v_exp_f32_e32 v109, v110
	v_add_f32_e32 v7, v106, v7
	v_exp_f32_e32 v110, v111
	v_add_f32_e32 v7, v107, v7
	v_exp_f32_e32 v111, v112
	v_add_f32_e32 v7, v108, v7
	v_exp_f32_e32 v112, v113
	v_add_f32_e32 v7, v109, v7
	v_add_f32_e32 v7, v110, v7
	v_add_f32_e32 v7, v111, v7
	v_cvt_pk_bf16_f32 v4, v2, v4
	v_add_f32_e32 v17, v112, v7
	v_cvt_pk_bf16_f32 v5, v5, v6
	v_cvt_pk_bf16_f32 v6, v8, v9
	v_cvt_pk_bf16_f32 v7, v10, v11
	v_cvt_pk_bf16_f32 v106, v16, v106
	v_cvt_pk_bf16_f32 v107, v107, v108
	v_cvt_pk_bf16_f32 v108, v109, v110
	v_cvt_pk_bf16_f32 v109, v111, v112
	s_branch .LBB0_1030

; #define LAS __attribute__((address_space(3)))
; #define ATT_WAIT(n) asm volatile("s_waitcnt vmcnt(" #n ")" ::: "memory")
; #define ATT_BAR() do { asm volatile("s_waitcnt lgkmcnt(0)" ::: "memory"); __builtin_amdgcn_s_barrier(); asm volatile("" ::: "memory"); } while (0)
; #define ATT_ISSUE_K() attn_issue_k(F, KH + (size_t)ATT_TILE((t + 2 < nt) ? t + 2 : nt - 1) * ATT_KB, lds + b2 * ATT_KB)
; #define ATT_ISSUE_V() attn_issue_v(F, VT + (size_t)ATT_TILE((t + 2 < nt) ? t + 2 : nt - 1) * ATT_VB, lds + ATT_VBASE + b2 * ATT_VB)
; #define ATT_ROT() do { bp = b0; b0 = (b0 == 2) ? 0 : b0 + 1; b2 = (b2 == 2) ? 0 : b2 + 1; } while (0)
; __device__ __forceinline__ void attn_issue_v(const Frame& F, const unsigned char* vtile, LAS unsigned char* buf) {
;     unsigned lo = F.lane * 16; asm volatile("" : "+v"(lo));
; #pragma unroll
;     for (int j = 0; j < 2; ++j) __builtin_amdgcn_global_load_lds((const unsigned*)(vtile + (size_t)(F.wave * 2 + j) * 1024 + lo), (LAS unsigned*)(buf + (F.wave * 2 + j) * 1024), 16, 0, 0);
; }
; __device__ __forceinline__ void attn_unit(const Frame& F, int h, int qb, const float* qw, bool desc) {
;     ...
;             ATT_ISSUE_K(); ATT_QK(tl, b0); ATT_WAIT(8); ATT_BAR();
;             ATT_ISSUE_V(); ATT_SMPV(tl, b0); ATT_WAIT(7); ATT_BAR();
;             ATT_ROT();
.LBB0_1030:
	s_lshl_b32 s75, s75, 14
	s_add_u32 s88, s42, s75
	s_addc_u32 s89, s43, 0
	s_lshl_b32 s75, s74, 14
	s_waitcnt vmcnt(8)
	s_add_i32 s75, s75, 0
	v_mov_b32_e32 v2, v164
	s_waitcnt lgkmcnt(0)
	s_barrier
	s_setprio 2
	s_add_i32 s75, s75, 0x12000
	s_add_i32 m0, s75, s59
	s_add_u32 s98, s88, s14
	s_addc_u32 s99, s89, s15
	global_load_lds_dwordx4 v164, s[98:99]
	s_add_u32 s100, s88, s16
	s_addc_u32 s101, s89, s17
	s_add_i32 m0, s75, s60
	s_andn2_b64 vcc, exec, s[0:1]
	global_load_lds_dwordx4 v164, s[100:101]
	s_cbranch_vccnz .LBB0_1026
	s_branch .LBB0_1025
